# conv and pooling: thread-to-task relabelling so the short fifth round of layer 0 lands on workgroups 448..511 instead of stacking on 0..63
# speedup vs baseline: 1.0055x; 1.0018x over previous
.LBB0_344:
	v_readlane_b32 s0, v205, 9
	v_readlane_b32 s1, v205, 10
	s_and_b64 s[0:1], s[0:1], exec
	s_cselect_b32 s2, 0x4200, s66
	v_mov_b32_e32 v0, v138
	v_readlane_b32 s0, v207, 36
	s_lshl_b32 s56, s2, 5
	s_lshl_b32 s8, s50, 8
	v_add_u32_e32 v60, s0, v0
	v_xor_b32_e32 v60, 0x1c000, v60
	s_mov_b32 s9, s19
	v_cmp_gt_i32_e32 vcc, s56, v60
	s_and_saveexec_b64 s[12:13], vcc
	s_cbranch_execz .LBB0_449
	v_readlane_b32 s0, v205, 18
	s_mul_i32 s18, s50, 0x300
	v_readlane_b32 s76, v207, 20
	s_lshl_b32 s57, s0, 8
	s_lshl_b64 s[0:1], s[18:19], 2
	v_readlane_b32 s82, v207, 26
	v_lshlrev_b32_e32 v36, 3, v0
	v_readlane_b32 s83, v207, 27
	s_add_u32 s0, s82, s0
	v_and_b32_e32 v34, 0xf8, v36
	v_readlane_b32 s84, v207, 28
	s_addc_u32 s1, s83, s1
	s_lshl_b64 s[16:17], s[8:9], 2
	v_readlane_b32 s85, v207, 29
	v_lshlrev_b32_e32 v28, 2, v34
	s_add_u32 s16, s84, s16
	s_addc_u32 s17, s85, s17
	global_load_dwordx4 v[0:3], v28, s[0:1] offset:16
	global_load_dwordx4 v[4:7], v28, s[0:1]
	global_load_dwordx4 v[8:11], v28, s[0:1] offset:1040
	global_load_dwordx4 v[12:15], v28, s[0:1] offset:1024
	global_load_dwordx4 v[16:19], v28, s[0:1] offset:2064
	global_load_dwordx4 v[20:23], v28, s[0:1] offset:2048
	global_load_dwordx4 v[24:27], v28, s[16:17] offset:16
	s_nop 0
	global_load_dwordx4 v[28:31], v28, s[16:17]
	v_readlane_b32 s0, v206, 43
	v_lshlrev_b32_e32 v134, 1, v34
	v_readlane_b32 s1, v206, 44
	s_mov_b64 s[16:17], 0
	v_lshlrev_b32_e32 v34, 1, v34
	v_lshl_add_u64 v[32:33], s[0:1], 0, v[134:135]
	v_mov_b32_e32 v37, v60
	s_movk_i32 s3, 0x4000
	v_readlane_b32 s77, v207, 21
	v_readlane_b32 s78, v207, 22
	v_readlane_b32 s79, v207, 23
	v_readlane_b32 s80, v207, 24
	v_readlane_b32 s81, v207, 25
	v_readlane_b32 s86, v207, 30
	v_readlane_b32 s87, v207, 31
	v_readlane_b32 s88, v207, 32
	v_readlane_b32 s89, v207, 33
	v_readlane_b32 s90, v207, 34
	v_readlane_b32 s91, v207, 35
